# P0 weight prep: gain-folding tile paths issued all 8 W + 8 g loads up front instead of 8 serialized round trips; plus P4 epilogue SSQ loads batched 4 row-groups ahead
# speedup vs baseline: 1.0501x; 1.0111x over previous
; DI unsigned cvtpk(float lo, float hi) { f32x2_t v = {lo, hi}; bf16x2_t b = __builtin_convertvector(v, bf16x2_t); return __builtin_bit_cast(unsigned, b); }
; DI int win_src(int n) { const int pn = n >> 8, c = n & 255; if (pn <= 3 || pn == 6 || pn == 7) { const int bj = c >> 7, j = (c >> 5) & 3, e = bj * 32 + (c & 31); return pn * 256 + j * 64 + e; } return n; }
; DI void p0_transpose_tile(const float* W0, const float* W1, int ldw, int K, const float* gk, bf16_t* Bt, int mode, int k0, int n0, LAS float* scr) {
;     ...
;     for (int i = 0; i < 8; ++i) { const int idx = tid + 512 * i, kk = idx >> 6, nn = idx & 63, n = n0 + nn;
;         const float* W = W0; int src = n;
;         if (mode == 1) src = win_src(n);
;         else if (mode == 2) { const int pn = n >> 8, c = n & 255; if (c >= 128) W = W1; src = pn * 128 + (c & 127); }
;         float v = W[(size_t)(k0 + kk) * ldw + src]; if (gk) v *= gk[k0 + kk];
;         scr[kk * 65 + nn] = v; }
;     __syncthreads();
;     { const int nn = tid >> 3, kg = (tid & 7) * 8;
;         u32x4 o; o.x = cvtpk(scr[(kg + 0) * 65 + nn], scr[(kg + 1) * 65 + nn]); o.y = cvtpk(scr[(kg + 2) * 65 + nn], scr[(kg + 3) * 65 + nn]);
;         o.z = cvtpk(scr[(kg + 4) * 65 + nn], scr[(kg + 5) * 65 + nn]); o.w = cvtpk(scr[(kg + 6) * 65 + nn], scr[(kg + 7) * 65 + nn]);
;         *(u32x4*)(Bt + (size_t)(n0 + nn) * K + k0 + kg) = o; }
;     __syncthreads();
.LBB0_2:
	v_lshlrev_b32_e32 v4, 3, v9
	v_ashrrev_i32_e32 v2, 3, v9
	v_and_b32_e32 v9, 56, v4
	v_mul_u32_u24_e32 v4, 0x104, v9
	v_lshlrev_b32_e32 v5, 2, v2
	v_add3_u32 v10, 0, v4, v5
	s_waitcnt lgkmcnt(0)
	s_barrier
	ds_read2_b32 v[4:5], v10 offset1:65
	ds_read2_b32 v[6:7], v10 offset0:130 offset1:195
	v_add_u32_e32 v12, 0x400, v10
	ds_read2_b32 v[10:11], v12 offset0:4 offset1:69
	ds_read2_b32 v[12:13], v12 offset0:134 offset1:199
	s_mulk_i32 s26, 0xc00
	v_subrev_u32_e32 v2, s26, v2
	s_waitcnt lgkmcnt(3)
	v_cvt_pk_bf16_f32 v4, v4, v5
	s_waitcnt lgkmcnt(2)
	v_cvt_pk_bf16_f32 v5, v6, v7
	s_waitcnt lgkmcnt(1)
	v_cvt_pk_bf16_f32 v6, v10, v11
	v_add_u32_e32 v10, s30, v2
	v_ashrrev_i32_e32 v11, 31, v10
	v_lshlrev_b64 v[10:11], 11, v[10:11]
	v_lshl_add_u64 v[10:11], s[20:21], 0, v[10:11]
	s_ashr_i32 s29, s28, 31
	v_lshl_add_u64 v[10:11], s[28:29], 1, v[10:11]
	v_lshlrev_b32_e32 v2, 1, v9
	s_waitcnt lgkmcnt(0)
	v_cvt_pk_bf16_f32 v7, v12, v13
	v_lshl_add_u64 v[10:11], v[10:11], 0, v[2:3]
	global_store_dwordx4 v[10:11], v[4:7], off
	s_barrier

; __device__ __forceinline__ int launder_tid() { int x = threadIdx.x; asm volatile("" : "+v"(x)); return x; }
; #define LAS __attribute__((address_space(3)))
; DI unsigned cvtpk(float lo, float hi) { f32x2_t v = {lo, hi}; bf16x2_t b = __builtin_convertvector(v, bf16x2_t); return __builtin_bit_cast(unsigned, b); }
; DI int win_src(int n) { const int pn = n >> 8, c = n & 255; if (pn <= 3 || pn == 6 || pn == 7) { const int bj = c >> 7, j = (c >> 5) & 3, e = bj * 32 + (c & 31); return pn * 256 + j * 64 + e; } return n; }
; DI void p0_transpose_tile(const float* W0, const float* W1, int ldw, int K, const float* gk, bf16_t* Bt, int mode, int k0, int n0, LAS float* scr) {
;     const int tid = launder_tid();
; #pragma unroll
;     for (int i = 0; i < 8; ++i) { const int idx = tid + 512 * i, kk = idx >> 6, nn = idx & 63, n = n0 + nn;
;         const float* W = W0; int src = n;
;         if (mode == 1) src = win_src(n);
;         else if (mode == 2) { const int pn = n >> 8, c = n & 255; if (c >= 128) W = W1; src = pn * 128 + (c & 127); }
;         float v = W[(size_t)(k0 + kk) * ldw + src]; if (gk) v *= gk[k0 + kk];
;         scr[kk * 65 + nn] = v; }
;     __syncthreads();
;     { const int nn = tid >> 3, kg = (tid & 7) * 8;
;         u32x4 o; o.x = cvtpk(scr[(kg + 0) * 65 + nn], scr[(kg + 1) * 65 + nn]); o.y = cvtpk(scr[(kg + 2) * 65 + nn], scr[(kg + 3) * 65 + nn]);
;         o.z = cvtpk(scr[(kg + 4) * 65 + nn], scr[(kg + 5) * 65 + nn]); o.w = cvtpk(scr[(kg + 6) * 65 + nn], scr[(kg + 7) * 65 + nn]);
;         *(u32x4*)(Bt + (size_t)(n0 + nn) * K + k0 + kg) = o; }
;     __syncthreads();
; DI void p0_prep(const Params& p, LAS unsigned char* lds) {
;     ...
;         else if (it < T_IN + T_OUT + T_GU) { const int j = it - T_IN - T_OUT, kt = j / 88, nt = j % 88; p0_transpose_tile(p.w_gate, p.w_up, DFF, DM, p.g_ffn, (bf16_t*)(ws + WS_WGU), 2, kt * 64, nt * 64, scr); }
.LBB0_8:
	s_andn2_b64 vcc, exec, s[4:5]
	s_cbranch_vccnz .LBB0_26
	s_add_i32 s4, s76, 0xfc00
	s_and_b32 s5, s4, 0xffff
	s_mul_i32 s5, s5, 0xba2f
	s_lshr_b32 s26, s5, 16
	s_lshr_b32 s5, s5, 22
	s_mulk_i32 s5, 0x58
	s_sub_i32 s4, s4, s5
	s_and_b32 s26, s26, 0xffc0
	s_lshl_b32 s77, s4, 6
	s_bitcmp0_b32 s77, 7
	s_cselect_b32 s29, s11, s13
	s_cselect_b32 s28, s10, s12
	s_lshl_b32 s4, s4, 5
	v_mov_b32_e32 v9, v182
	s_and_b32 s4, s4, 0xf80
	s_and_b32 s5, s77, 64
	s_or_b32 s4, s4, s5
	v_and_b32_e32 v7, 63, v9
	v_ashrrev_i32_e32 v10, 6, v9
	v_or_b32_e32 v2, s4, v7
	v_add_u32_e32 v4, s26, v10
	v_mov_b64_e32 v[12:13], s[28:29]
	v_mad_i64_i32 v[12:13], s[4:5], v4, s38, v[12:13]
	v_lshlrev_b32_e32 v2, 2, v2
	v_lshl_add_u64 v[12:13], v[12:13], 0, v[2:3]
	s_lshl_b32 s78, s38, 3
	s_mov_b32 s79, 0
	v_ashrrev_i32_e32 v5, 31, v4
	v_lshl_add_u64 v[14:15], v[4:5], 2, s[8:9]
	global_load_dword v100, v[12:13], off
	v_lshl_add_u64 v[12:13], v[12:13], 0, s[78:79]
	global_load_dword v101, v[12:13], off
	v_lshl_add_u64 v[12:13], v[12:13], 0, s[78:79]
	global_load_dword v102, v[12:13], off
	v_lshl_add_u64 v[12:13], v[12:13], 0, s[78:79]
	global_load_dword v103, v[12:13], off
	v_lshl_add_u64 v[12:13], v[12:13], 0, s[78:79]
	global_load_dword v104, v[12:13], off
	v_lshl_add_u64 v[12:13], v[12:13], 0, s[78:79]
	global_load_dword v105, v[12:13], off
	v_lshl_add_u64 v[12:13], v[12:13], 0, s[78:79]
	global_load_dword v106, v[12:13], off
	v_lshl_add_u64 v[12:13], v[12:13], 0, s[78:79]
	global_load_dword v107, v[12:13], off
	s_andn2_b64 vcc, exec, s[22:23]
	s_cbranch_vccnz .Lp0m2_nog
	global_load_dword v108, v[14:15], off
	global_load_dword v109, v[14:15], off offset:32
	global_load_dword v110, v[14:15], off offset:64
	global_load_dword v111, v[14:15], off offset:96
	global_load_dword v112, v[14:15], off offset:128
	global_load_dword v113, v[14:15], off offset:160
	global_load_dword v114, v[14:15], off offset:192
	global_load_dword v115, v[14:15], off offset:224
	s_waitcnt vmcnt(0)
	v_mul_f32_e32 v100, v100, v108
	v_mul_f32_e32 v101, v101, v109
	v_mul_f32_e32 v102, v102, v110
	v_mul_f32_e32 v103, v103, v111
	v_mul_f32_e32 v104, v104, v112
	v_mul_f32_e32 v105, v105, v113
	v_mul_f32_e32 v106, v106, v114
	v_mul_f32_e32 v107, v107, v115
.Lp0m2_nog:
	s_waitcnt vmcnt(0)
	v_mul_u32_u24_e32 v14, 0x104, v10
	v_lshl_add_u32 v14, v7, 2, v14
	ds_write_b32 v14, v100
	ds_write_b32 v14, v101 offset:2080
	ds_write_b32 v14, v102 offset:4160
	ds_write_b32 v14, v103 offset:6240
	ds_write_b32 v14, v104 offset:8320
	ds_write_b32 v14, v105 offset:10400
	ds_write_b32 v14, v106 offset:12480
	ds_write_b32 v14, v107 offset:14560
	v_lshlrev_b32_e32 v4, 3, v9
	v_ashrrev_i32_e32 v2, 3, v9
	v_and_b32_e32 v9, 56, v4
	v_mul_u32_u24_e32 v4, 0x104, v9
	v_lshlrev_b32_e32 v5, 2, v2
	v_add3_u32 v10, 0, v4, v5
	s_waitcnt lgkmcnt(0)
	s_barrier
	ds_read2_b32 v[4:5], v10 offset1:65
	ds_read2_b32 v[6:7], v10 offset0:130 offset1:195
	v_add_u32_e32 v12, 0x400, v10
	ds_read2_b32 v[10:11], v12 offset0:4 offset1:69
	ds_read2_b32 v[12:13], v12 offset0:134 offset1:199
	s_and_b32 s4, s77, 0xffc0
	s_waitcnt lgkmcnt(3)
	v_cvt_pk_bf16_f32 v4, v4, v5
	s_waitcnt lgkmcnt(2)
	v_cvt_pk_bf16_f32 v5, v6, v7
	s_waitcnt lgkmcnt(1)
	v_cvt_pk_bf16_f32 v6, v10, v11
	v_add_u32_e32 v10, s4, v2
	v_ashrrev_i32_e32 v11, 31, v10
	v_lshlrev_b64 v[10:11], 11, v[10:11]
	v_lshl_add_u64 v[10:11], s[16:17], 0, v[10:11]
	s_lshl_b32 s26, s26, 1
	v_lshl_add_u64 v[10:11], v[10:11], 0, s[26:27]
	v_lshlrev_b32_e32 v2, 1, v9
	s_waitcnt lgkmcnt(0)
	v_cvt_pk_bf16_f32 v7, v12, v13
	v_lshl_add_u64 v[10:11], v[10:11], 0, v[2:3]
	global_store_dwordx4 v[10:11], v[4:7], off
	s_barrier

; __device__ __forceinline__ int launder_tid() { int x = threadIdx.x; asm volatile("" : "+v"(x)); return x; }
; #define LAS __attribute__((address_space(3)))
; DI int win_src(int n) { const int pn = n >> 8, c = n & 255; if (pn <= 3 || pn == 6 || pn == 7) { const int bj = c >> 7, j = (c >> 5) & 3, e = bj * 32 + (c & 31); return pn * 256 + j * 64 + e; } return n; }
; DI void p0_transpose_tile(const float* W0, const float* W1, int ldw, int K, const float* gk, bf16_t* Bt, int mode, int k0, int n0, LAS float* scr) {
;     const int tid = launder_tid();
; #pragma unroll
;     for (int i = 0; i < 8; ++i) { const int idx = tid + 512 * i, kk = idx >> 6, nn = idx & 63, n = n0 + nn;
;         const float* W = W0; int src = n;
;         if (mode == 1) src = win_src(n);
;         else if (mode == 2) { const int pn = n >> 8, c = n & 255; if (c >= 128) W = W1; src = pn * 128 + (c & 127); }
;         float v = W[(size_t)(k0 + kk) * ldw + src]; if (gk) v *= gk[k0 + kk];
;         scr[kk * 65 + nn] = v; }
; DI void p0_prep(const Params& p, LAS unsigned char* lds) {
;     ...
;         if (it < T_IN) { const int kt = it / 48, nt = it % 48; p0_transpose_tile(p.w_in, nullptr, PIN, DM, p.g_mix, (bf16_t*)(ws + WS_WIN), 1, kt * 64, nt * 64, scr); }
.LBB0_30:
	s_andn2_b64 vcc, exec, s[4:5]
	s_cbranch_vccnz .LBB0_3
	s_mul_hi_i32 s4, s76, 0x2aaaaaab
	s_lshr_b32 s5, s4, 31
	s_ashr_i32 s26, s4, 3
	s_add_i32 s26, s26, s5
	s_mul_i32 s4, s26, 0xffffffd0
	s_add_i32 s4, s76, s4
	s_mul_i32 s5, s26, 0xfffff400
	v_mov_b32_e32 v9, v182
	s_lshl_b32 s28, s26, 6
	s_add_i32 s29, s30, s5
	s_and_b32 s4, s4, 0x3fffff8
	v_and_b32_e32 v2, 63, v9
	v_add_u32_e32 v4, s29, v2
	s_cmp_eq_u32 s4, 24
	s_cselect_b64 s[4:5], -1, 0
	s_lshr_b32 s29, s29, 2
	v_lshlrev_b32_e32 v5, 1, v4
	v_cmp_gt_i32_e32 vcc, s36, v4
	s_and_b32 s29, s29, 32
	v_and_b32_e32 v5, 0xc0, v5
	v_and_b32_e32 v6, 0xffffff1f, v4
	v_or3_b32 v5, v6, s29, v5
	s_or_b64 vcc, s[4:5], vcc
	v_ashrrev_i32_e32 v10, 6, v9
	v_cndmask_b32_e32 v4, v4, v5, vcc
	v_add_u32_e32 v6, s28, v10
	v_mov_b64_e32 v[12:13], s[54:55]
	v_ashrrev_i32_e32 v5, 31, v4
	v_mad_i64_i32 v[12:13], s[4:5], v6, s39, v[12:13]
	v_lshl_add_u64 v[12:13], v[4:5], 2, v[12:13]
	s_lshl_b32 s78, s39, 3
	s_mov_b32 s79, 0
	v_ashrrev_i32_e32 v7, 31, v6
	v_lshl_add_u64 v[14:15], v[6:7], 2, s[52:53]
	global_load_dword v100, v[12:13], off
	v_lshl_add_u64 v[12:13], v[12:13], 0, s[78:79]
	global_load_dword v101, v[12:13], off
	v_lshl_add_u64 v[12:13], v[12:13], 0, s[78:79]
	global_load_dword v102, v[12:13], off
	v_lshl_add_u64 v[12:13], v[12:13], 0, s[78:79]
	global_load_dword v103, v[12:13], off
	v_lshl_add_u64 v[12:13], v[12:13], 0, s[78:79]
	global_load_dword v104, v[12:13], off
	v_lshl_add_u64 v[12:13], v[12:13], 0, s[78:79]
	global_load_dword v105, v[12:13], off
	v_lshl_add_u64 v[12:13], v[12:13], 0, s[78:79]
	global_load_dword v106, v[12:13], off
	v_lshl_add_u64 v[12:13], v[12:13], 0, s[78:79]
	global_load_dword v107, v[12:13], off
	s_andn2_b64 vcc, exec, s[24:25]
	s_cbranch_vccnz .Lp0m1_nog
	global_load_dword v108, v[14:15], off
	global_load_dword v109, v[14:15], off offset:32
	global_load_dword v110, v[14:15], off offset:64
	global_load_dword v111, v[14:15], off offset:96
	global_load_dword v112, v[14:15], off offset:128
	global_load_dword v113, v[14:15], off offset:160
	global_load_dword v114, v[14:15], off offset:192
	global_load_dword v115, v[14:15], off offset:224
	s_waitcnt vmcnt(0)
	v_mul_f32_e32 v100, v100, v108
	v_mul_f32_e32 v101, v101, v109
	v_mul_f32_e32 v102, v102, v110
	v_mul_f32_e32 v103, v103, v111
	v_mul_f32_e32 v104, v104, v112
	v_mul_f32_e32 v105, v105, v113
	v_mul_f32_e32 v106, v106, v114
	v_mul_f32_e32 v107, v107, v115
.Lp0m1_nog:
	s_waitcnt vmcnt(0)
	v_mul_u32_u24_e32 v14, 0x104, v10
	v_lshl_add_u32 v14, v2, 2, v14
	ds_write_b32 v14, v100
	ds_write_b32 v14, v101 offset:2080
	ds_write_b32 v14, v102 offset:4160
	ds_write_b32 v14, v103 offset:6240
	ds_write_b32 v14, v104 offset:8320
	ds_write_b32 v14, v105 offset:10400
	ds_write_b32 v14, v106 offset:12480
	ds_write_b32 v14, v107 offset:14560
	s_branch .LBB0_2

; DI unsigned cvtpk(float lo, float hi) { f32x2_t v = {lo, hi}; bf16x2_t b = __builtin_convertvector(v, bf16x2_t); return __builtin_bit_cast(unsigned, b); }
; DI float silu_f(float x) { return x * __builtin_amdgcn_rcpf(1.0f + __expf(-x)); }
;     DI void operator()(const f32x4 (&acc)[2][2][4][2], const Unit& u, int wr, int wc, int fr, int fq) const {
;     ...
;         for (int ai = 0; ai < 2; ++ai)
; #pragma unroll
;             for (int m = 0; m < 4; ++m) {
;                 const int row = u.pm * 256 + 128 * ai + 64 * wr + 16 * m + fr;
;                 const float* sp = SSQ + (size_t)row * 16;
;                 const f32x4 s0 = *(const f32x4*)sp, s1 = *(const f32x4*)(sp + 4), s2 = *(const f32x4*)(sp + 8), s3 = *(const f32x4*)(sp + 12);
;                 float ss = 0.f;
; #pragma unroll
;                 for (int i = 0; i < 4; ++i) ss += s0[i] + s1[i] + s2[i] + s3[i];
;                 const float rs = rsqrtf(ss * (1.0f / DM) + EPS);
;                 float a[8];
; #pragma unroll
;                 for (int n = 0; n < 2; ++n)
; #pragma unroll
;                     for (int t = 0; t < 4; ++t) a[4 * n + t] = silu_f(acc[ai][0][m][n][t] * rs) * (acc[ai][1][m][n][t] * rs);
;                 u32x4 w; w.x = cvtpk(a[0], a[1]); w.y = cvtpk(a[2], a[3]); w.z = cvtpk(a[4], a[5]); w.w = cvtpk(a[6], a[7]);
;                 __builtin_nontemporal_store(w, (u32x4*)(ACT + (size_t)row * DFF + u.pn * 128 + 32 * wc + 8 * fq));
.LBB0_863:
	v_lshl_add_u32 v148, s24, 8, v150
	v_ashrrev_i32_e32 v149, 31, v148
	v_lshlrev_b64 v[146:147], 6, v[148:149]
	v_lshl_add_u64 v[146:147], s[0:1], 0, v[146:147]
	global_load_dwordx4 v[186:189], v[146:147], off
	global_load_dwordx4 v[190:193], v[146:147], off offset:16
	global_load_dwordx4 v[194:197], v[146:147], off offset:32
	global_load_dwordx4 v[198:201], v[146:147], off offset:48
	global_load_dwordx4 v[202:205], v[146:147], off offset:1024
	global_load_dwordx4 v[206:209], v[146:147], off offset:1040
	global_load_dwordx4 v[210:213], v[146:147], off offset:1056
	global_load_dwordx4 v[214:217], v[146:147], off offset:1072
	global_load_dwordx4 v[218:221], v[146:147], off offset:2048
	global_load_dwordx4 v[222:225], v[146:147], off offset:2064
	global_load_dwordx4 v[226:229], v[146:147], off offset:2080
	global_load_dwordx4 v[230:233], v[146:147], off offset:2096
	global_load_dwordx4 v[234:237], v[146:147], off offset:3072
	global_load_dwordx4 v[238:241], v[146:147], off offset:3088
	global_load_dwordx4 v[242:245], v[146:147], off offset:3104
	global_load_dwordx4 v[246:249], v[146:147], off offset:3120
	v_add_co_u32_e32 v250, vcc, 0x2000, v146
	s_nop 1
	v_addc_co_u32_e32 v251, vcc, 0, v147, vcc
	s_lshl_b32 s24, s25, 7
	v_mov_b64_e32 v[146:147], s[52:53]
	s_ashr_i32 s25, s24, 31
	v_mad_i64_i32 v[172:173], s[26:27], v148, s48, v[146:147]
	s_lshl_b64 s[24:25], s[24:25], 1
	v_lshl_add_u64 v[172:173], v[172:173], 0, s[24:25]
	v_or_b32_e32 v174, 16, v148
	v_ashrrev_i32_e32 v175, 31, v174
	v_lshlrev_b64 v[176:177], 6, v[174:175]
	s_waitcnt vmcnt(12)
	v_pk_add_f32 v[156:157], v[186:187], v[190:191]
	s_nop 0
	v_pk_add_f32 v[156:157], v[194:195], v[156:157]
	v_pk_add_f32 v[158:159], v[188:189], v[192:193]
	v_pk_add_f32 v[156:157], v[198:199], v[156:157]
	v_pk_add_f32 v[158:159], v[196:197], v[158:159]
	v_add_f32_e32 v149, 0, v156
	v_pk_add_f32 v[158:159], v[200:201], v[158:159]
	global_load_dwordx4 v[186:189], v[250:251], off
	global_load_dwordx4 v[190:193], v[250:251], off offset:16
	global_load_dwordx4 v[194:197], v[250:251], off offset:32
	global_load_dwordx4 v[198:201], v[250:251], off offset:48
	v_add_f32_e32 v149, v157, v149
	v_add_f32_e32 v149, v158, v149
	v_add_f32_e32 v149, v159, v149
	v_fmamk_f32 v149, v149, 0x3a800000, v155
	v_mul_f32_e32 v156, 0x4b800000, v149
	v_cmp_gt_f32_e32 vcc, s47, v149
	v_lshl_add_u64 v[158:159], s[0:1], 0, v[176:177]
	s_nop 0
	v_cndmask_b32_e32 v149, v149, v156, vcc
	v_rsq_f32_e32 v149, v149
	v_lshl_add_u64 v[156:157], v[172:173], 0, s[8:9]
	v_lshl_add_u64 v[156:157], v[156:157], 0, v[136:137]
	v_mul_f32_e32 v160, 0x45800000, v149
	v_cndmask_b32_e32 v160, v149, v160, vcc
	v_pk_mul_f32 v[124:125], v[124:125], v[160:161] op_sel_hi:[1,0]
	v_pk_mul_f32 v[126:127], v[126:127], v[160:161] op_sel_hi:[1,0]
	v_pk_mul_f32 v[120:121], v[120:121], v[160:161] op_sel_hi:[1,0]
	v_pk_mul_f32 v[122:123], v[122:123], v[160:161] op_sel_hi:[1,0]
	v_pk_mul_f32 v[116:117], v[116:117], v[160:161] op_sel_hi:[1,0]
	v_pk_mul_f32 v[118:119], v[118:119], v[160:161] op_sel_hi:[1,0]
	v_pk_mul_f32 v[112:113], v[112:113], v[160:161] op_sel_hi:[1,0]
	v_pk_mul_f32 v[114:115], v[114:115], v[160:161] op_sel_hi:[1,0]
	v_mul_f32_e32 v149, 0xbfb8aa3b, v124
	v_mul_f32_e32 v160, 0xbfb8aa3b, v125
	v_mul_f32_e32 v161, 0xbfb8aa3b, v126
	v_mul_f32_e32 v162, 0xbfb8aa3b, v127
	v_mul_f32_e32 v163, 0xbfb8aa3b, v120
	v_mul_f32_e32 v164, 0xbfb8aa3b, v121
	v_mul_f32_e32 v165, 0xbfb8aa3b, v122
	v_mul_f32_e32 v166, 0xbfb8aa3b, v123
	v_exp_f32_e32 v149, v149
	v_exp_f32_e32 v160, v160
	v_exp_f32_e32 v161, v161
	v_exp_f32_e32 v162, v162
	v_exp_f32_e32 v163, v163
	v_exp_f32_e32 v164, v164
	v_exp_f32_e32 v165, v165
	v_exp_f32_e32 v166, v166
	v_add_f32_e32 v149, 1.0, v149
	v_add_f32_e32 v167, 1.0, v160
	v_add_f32_e32 v168, 1.0, v161
	v_add_f32_e32 v169, 1.0, v162
	v_add_f32_e32 v170, 1.0, v163
	v_add_f32_e32 v171, 1.0, v164
	v_add_f32_e32 v172, 1.0, v165
	v_add_f32_e32 v173, 1.0, v166
	v_rcp_f32_e32 v160, v149
	v_rcp_f32_e32 v161, v167
	v_rcp_f32_e32 v162, v168
	v_rcp_f32_e32 v163, v169
	v_rcp_f32_e32 v164, v170
	v_rcp_f32_e32 v165, v171
	v_rcp_f32_e32 v166, v172
	v_rcp_f32_e32 v167, v173
	v_pk_mul_f32 v[124:125], v[124:125], v[160:161]
	v_pk_mul_f32 v[126:127], v[126:127], v[162:163]
	v_pk_mul_f32 v[120:121], v[120:121], v[164:165]
	v_pk_mul_f32 v[122:123], v[122:123], v[166:167]
	v_pk_mul_f32 v[116:117], v[116:117], v[124:125]
	v_pk_mul_f32 v[118:119], v[118:119], v[126:127]
	v_pk_mul_f32 v[120:121], v[112:113], v[120:121]
	v_pk_mul_f32 v[122:123], v[114:115], v[122:123]
	v_cvt_pk_bf16_f32 v112, v116, v117
	v_cvt_pk_bf16_f32 v113, v118, v119
	v_cvt_pk_bf16_f32 v114, v120, v121
	v_cvt_pk_bf16_f32 v115, v122, v123
	global_store_dwordx4 v[156:157], v[112:115], off nt
	v_mad_i64_i32 v[158:159], s[26:27], v174, s48, v[146:147]
	v_or_b32_e32 v156, 32, v148
	v_lshl_add_u64 v[158:159], v[158:159], 0, s[24:25]
	v_ashrrev_i32_e32 v157, 31, v156
	v_lshlrev_b64 v[160:161], 6, v[156:157]
	s_waitcnt vmcnt(13)
; DI unsigned cvtpk(float lo, float hi) { f32x2_t v = {lo, hi}; bf16x2_t b = __builtin_convertvector(v, bf16x2_t); return __builtin_bit_cast(unsigned, b); }
; DI float silu_f(float x) { return x * __builtin_amdgcn_rcpf(1.0f + __expf(-x)); }
;     DI void operator()(const f32x4 (&acc)[2][2][4][2], const Unit& u, int wr, int wc, int fr, int fq) const {
;     ...
;         for (int ai = 0; ai < 2; ++ai)
; #pragma unroll
;             for (int m = 0; m < 4; ++m) {
;                 const int row = u.pm * 256 + 128 * ai + 64 * wr + 16 * m + fr;
;                 const float* sp = SSQ + (size_t)row * 16;
;                 const f32x4 s0 = *(const f32x4*)sp, s1 = *(const f32x4*)(sp + 4), s2 = *(const f32x4*)(sp + 8), s3 = *(const f32x4*)(sp + 12);
;                 float ss = 0.f;
; #pragma unroll
;                 for (int i = 0; i < 4; ++i) ss += s0[i] + s1[i] + s2[i] + s3[i];
;                 const float rs = rsqrtf(ss * (1.0f / DM) + EPS);
;                 float a[8];
; #pragma unroll
;                 for (int n = 0; n < 2; ++n)
; #pragma unroll
;                     for (int t = 0; t < 4; ++t) a[4 * n + t] = silu_f(acc[ai][0][m][n][t] * rs) * (acc[ai][1][m][n][t] * rs);
;                 u32x4 w; w.x = cvtpk(a[0], a[1]); w.y = cvtpk(a[2], a[3]); w.z = cvtpk(a[4], a[5]); w.w = cvtpk(a[6], a[7]);
;                 __builtin_nontemporal_store(w, (u32x4*)(ACT + (size_t)row * DFF + u.pn * 128 + 32 * wc + 8 * fq));
	v_pk_add_f32 v[112:113], v[202:203], v[206:207]
	v_pk_add_f32 v[112:113], v[210:211], v[112:113]
	v_pk_add_f32 v[114:115], v[204:205], v[208:209]
	v_pk_add_f32 v[112:113], v[214:215], v[112:113]
	v_pk_add_f32 v[114:115], v[212:213], v[114:115]
	v_add_f32_e32 v112, 0, v112
	v_pk_add_f32 v[114:115], v[216:217], v[114:115]
	global_load_dwordx4 v[202:205], v[250:251], off offset:1024
	global_load_dwordx4 v[206:209], v[250:251], off offset:1040
	global_load_dwordx4 v[210:213], v[250:251], off offset:1056
	global_load_dwordx4 v[214:217], v[250:251], off offset:1072
	v_add_f32_e32 v112, v113, v112
	v_add_f32_e32 v112, v114, v112
	v_add_f32_e32 v112, v115, v112
	v_fmamk_f32 v112, v112, 0x3a800000, v155
	v_mul_f32_e32 v113, 0x4b800000, v112
	v_cmp_gt_f32_e32 vcc, s47, v112
	v_lshl_add_u64 v[114:115], s[0:1], 0, v[160:161]
	s_nop 0
	v_cndmask_b32_e32 v112, v112, v113, vcc
	v_rsq_f32_e32 v116, v112
	v_lshl_add_u64 v[112:113], v[158:159], 0, s[8:9]
	v_lshl_add_u64 v[112:113], v[112:113], 0, v[136:137]
	v_mul_f32_e32 v117, 0x45800000, v116
	v_cndmask_b32_e32 v116, v116, v117, vcc
	v_pk_mul_f32 v[108:109], v[108:109], v[116:117] op_sel_hi:[1,0]
	v_pk_mul_f32 v[110:111], v[110:111], v[116:117] op_sel_hi:[1,0]
	v_pk_mul_f32 v[104:105], v[104:105], v[116:117] op_sel_hi:[1,0]
	v_pk_mul_f32 v[106:107], v[106:107], v[116:117] op_sel_hi:[1,0]
	v_pk_mul_f32 v[100:101], v[100:101], v[116:117] op_sel_hi:[1,0]
	v_pk_mul_f32 v[102:103], v[102:103], v[116:117] op_sel_hi:[1,0]
	v_pk_mul_f32 v[96:97], v[96:97], v[116:117] op_sel_hi:[1,0]
	v_pk_mul_f32 v[98:99], v[98:99], v[116:117] op_sel_hi:[1,0]
	v_mul_f32_e32 v116, 0xbfb8aa3b, v108
	v_mul_f32_e32 v117, 0xbfb8aa3b, v109
	v_mul_f32_e32 v118, 0xbfb8aa3b, v110
	v_mul_f32_e32 v119, 0xbfb8aa3b, v111
	v_mul_f32_e32 v120, 0xbfb8aa3b, v104
	v_mul_f32_e32 v121, 0xbfb8aa3b, v105
	v_mul_f32_e32 v122, 0xbfb8aa3b, v106
	v_mul_f32_e32 v123, 0xbfb8aa3b, v107
	v_exp_f32_e32 v116, v116
	v_exp_f32_e32 v117, v117
	v_exp_f32_e32 v118, v118
	v_exp_f32_e32 v119, v119
	v_exp_f32_e32 v120, v120
	v_exp_f32_e32 v121, v121
	v_exp_f32_e32 v122, v122
	v_exp_f32_e32 v123, v123
	v_add_f32_e32 v116, 1.0, v116
	v_add_f32_e32 v117, 1.0, v117
	v_add_f32_e32 v118, 1.0, v118
	v_add_f32_e32 v119, 1.0, v119
	v_add_f32_e32 v120, 1.0, v120
	v_add_f32_e32 v121, 1.0, v121
	v_add_f32_e32 v122, 1.0, v122
	v_add_f32_e32 v123, 1.0, v123
	v_rcp_f32_e32 v116, v116
	v_rcp_f32_e32 v117, v117
	v_rcp_f32_e32 v118, v118
	v_rcp_f32_e32 v119, v119
	v_rcp_f32_e32 v120, v120
	v_rcp_f32_e32 v121, v121
	v_rcp_f32_e32 v122, v122
	v_rcp_f32_e32 v123, v123
	v_pk_mul_f32 v[108:109], v[108:109], v[116:117]
	v_pk_mul_f32 v[110:111], v[110:111], v[118:119]
	v_pk_mul_f32 v[104:105], v[104:105], v[120:121]
	v_pk_mul_f32 v[106:107], v[106:107], v[122:123]
	v_pk_mul_f32 v[100:101], v[100:101], v[108:109]
	v_pk_mul_f32 v[102:103], v[102:103], v[110:111]
	v_pk_mul_f32 v[104:105], v[96:97], v[104:105]
	v_pk_mul_f32 v[106:107], v[98:99], v[106:107]
	v_cvt_pk_bf16_f32 v96, v100, v101
	v_cvt_pk_bf16_f32 v97, v102, v103
	v_cvt_pk_bf16_f32 v98, v104, v105
	v_cvt_pk_bf16_f32 v99, v106, v107
	global_store_dwordx4 v[112:113], v[96:99], off nt
	v_mad_i64_i32 v[114:115], s[26:27], v156, s48, v[146:147]
	v_or_b32_e32 v112, 48, v148
	v_lshl_add_u64 v[114:115], v[114:115], 0, s[24:25]
	v_ashrrev_i32_e32 v113, 31, v112
	v_lshlrev_b64 v[116:117], 6, v[112:113]
	s_waitcnt vmcnt(14)
	v_pk_add_f32 v[96:97], v[218:219], v[222:223]
	v_pk_add_f32 v[96:97], v[226:227], v[96:97]
	v_pk_add_f32 v[98:99], v[220:221], v[224:225]
	v_pk_add_f32 v[96:97], v[230:231], v[96:97]
	v_pk_add_f32 v[98:99], v[228:229], v[98:99]
	v_add_f32_e32 v96, 0, v96
	v_pk_add_f32 v[98:99], v[232:233], v[98:99]
	global_load_dwordx4 v[218:221], v[250:251], off offset:2048
	global_load_dwordx4 v[222:225], v[250:251], off offset:2064
	global_load_dwordx4 v[226:229], v[250:251], off offset:2080
	global_load_dwordx4 v[230:233], v[250:251], off offset:2096
	v_add_f32_e32 v96, v97, v96
	v_add_f32_e32 v96, v98, v96
	v_add_f32_e32 v96, v99, v96
	v_fmamk_f32 v96, v96, 0x3a800000, v155
	v_mul_f32_e32 v97, 0x4b800000, v96
	v_cmp_gt_f32_e32 vcc, s47, v96
	v_lshl_add_u64 v[98:99], s[0:1], 0, v[116:117]
	s_nop 0
	v_cndmask_b32_e32 v96, v96, v97, vcc
	v_rsq_f32_e32 v100, v96
	v_lshl_add_u64 v[96:97], v[114:115], 0, s[8:9]
	v_lshl_add_u64 v[96:97], v[96:97], 0, v[136:137]
	v_mul_f32_e32 v101, 0x45800000, v100
	v_cndmask_b32_e32 v100, v100, v101, vcc
	v_pk_mul_f32 v[92:93], v[92:93], v[100:101] op_sel_hi:[1,0]
	v_pk_mul_f32 v[94:95], v[94:95], v[100:101] op_sel_hi:[1,0]
	v_pk_mul_f32 v[88:89], v[88:89], v[100:101] op_sel_hi:[1,0]
	v_pk_mul_f32 v[90:91], v[90:91], v[100:101] op_sel_hi:[1,0]
	v_pk_mul_f32 v[84:85], v[84:85], v[100:101] op_sel_hi:[1,0]
	v_pk_mul_f32 v[86:87], v[86:87], v[100:101] op_sel_hi:[1,0]
	v_pk_mul_f32 v[80:81], v[80:81], v[100:101] op_sel_hi:[1,0]
	v_pk_mul_f32 v[82:83], v[82:83], v[100:101] op_sel_hi:[1,0]
	v_mul_f32_e32 v100, 0xbfb8aa3b, v92
	v_mul_f32_e32 v101, 0xbfb8aa3b, v93
	v_mul_f32_e32 v102, 0xbfb8aa3b, v94
	v_mul_f32_e32 v103, 0xbfb8aa3b, v95
	v_mul_f32_e32 v104, 0xbfb8aa3b, v88
	v_mul_f32_e32 v105, 0xbfb8aa3b, v89
	v_mul_f32_e32 v106, 0xbfb8aa3b, v90
	v_mul_f32_e32 v107, 0xbfb8aa3b, v91
	v_exp_f32_e32 v100, v100
	v_exp_f32_e32 v101, v101
	v_exp_f32_e32 v102, v102
	v_exp_f32_e32 v103, v103
	v_exp_f32_e32 v104, v104
	v_exp_f32_e32 v105, v105
	v_exp_f32_e32 v106, v106
	v_exp_f32_e32 v107, v107
	v_add_f32_e32 v100, 1.0, v100
	v_add_f32_e32 v101, 1.0, v101
	v_add_f32_e32 v102, 1.0, v102
	v_add_f32_e32 v103, 1.0, v103
	v_add_f32_e32 v104, 1.0, v104
	v_add_f32_e32 v105, 1.0, v105
	v_add_f32_e32 v106, 1.0, v106
	v_add_f32_e32 v107, 1.0, v107
	v_rcp_f32_e32 v100, v100
	v_rcp_f32_e32 v101, v101
	v_rcp_f32_e32 v102, v102
	v_rcp_f32_e32 v103, v103
	v_rcp_f32_e32 v104, v104
	v_rcp_f32_e32 v105, v105
	v_rcp_f32_e32 v106, v106
	v_rcp_f32_e32 v107, v107
	v_pk_mul_f32 v[92:93], v[92:93], v[100:101]
	v_pk_mul_f32 v[94:95], v[94:95], v[102:103]
	v_pk_mul_f32 v[88:89], v[88:89], v[104:105]
	v_pk_mul_f32 v[90:91], v[90:91], v[106:107]
	v_pk_mul_f32 v[84:85], v[84:85], v[92:93]
	v_pk_mul_f32 v[86:87], v[86:87], v[94:95]
	v_pk_mul_f32 v[88:89], v[80:81], v[88:89]
	v_pk_mul_f32 v[90:91], v[82:83], v[90:91]
	v_cvt_pk_bf16_f32 v80, v84, v85
	v_cvt_pk_bf16_f32 v81, v86, v87
	v_cvt_pk_bf16_f32 v82, v88, v89
	v_cvt_pk_bf16_f32 v83, v90, v91
	global_store_dwordx4 v[96:97], v[80:83], off nt
	v_mad_i64_i32 v[98:99], s[26:27], v112, s48, v[146:147]
	v_add_u32_e32 v96, 0x80, v148
	v_lshl_add_u64 v[98:99], v[98:99], 0, s[24:25]
	v_ashrrev_i32_e32 v97, 31, v96
	v_lshlrev_b64 v[100:101], 6, v[96:97]
	s_waitcnt vmcnt(15)
; DI unsigned cvtpk(float lo, float hi) { f32x2_t v = {lo, hi}; bf16x2_t b = __builtin_convertvector(v, bf16x2_t); return __builtin_bit_cast(unsigned, b); }
; DI float silu_f(float x) { return x * __builtin_amdgcn_rcpf(1.0f + __expf(-x)); }
;     DI void operator()(const f32x4 (&acc)[2][2][4][2], const Unit& u, int wr, int wc, int fr, int fq) const {
;     ...
;         for (int ai = 0; ai < 2; ++ai)
; #pragma unroll
;             for (int m = 0; m < 4; ++m) {
;                 const int row = u.pm * 256 + 128 * ai + 64 * wr + 16 * m + fr;
;                 const float* sp = SSQ + (size_t)row * 16;
;                 const f32x4 s0 = *(const f32x4*)sp, s1 = *(const f32x4*)(sp + 4), s2 = *(const f32x4*)(sp + 8), s3 = *(const f32x4*)(sp + 12);
;                 float ss = 0.f;
; #pragma unroll
;                 for (int i = 0; i < 4; ++i) ss += s0[i] + s1[i] + s2[i] + s3[i];
;                 const float rs = rsqrtf(ss * (1.0f / DM) + EPS);
;                 float a[8];
; #pragma unroll
;                 for (int n = 0; n < 2; ++n)
; #pragma unroll
;                     for (int t = 0; t < 4; ++t) a[4 * n + t] = silu_f(acc[ai][0][m][n][t] * rs) * (acc[ai][1][m][n][t] * rs);
;                 u32x4 w; w.x = cvtpk(a[0], a[1]); w.y = cvtpk(a[2], a[3]); w.z = cvtpk(a[4], a[5]); w.w = cvtpk(a[6], a[7]);
;                 __builtin_nontemporal_store(w, (u32x4*)(ACT + (size_t)row * DFF + u.pn * 128 + 32 * wc + 8 * fq));
	v_pk_add_f32 v[80:81], v[234:235], v[238:239]
	v_pk_add_f32 v[80:81], v[242:243], v[80:81]
	v_pk_add_f32 v[82:83], v[236:237], v[240:241]
	v_pk_add_f32 v[80:81], v[246:247], v[80:81]
	v_pk_add_f32 v[82:83], v[244:245], v[82:83]
	v_add_f32_e32 v80, 0, v80
	v_pk_add_f32 v[82:83], v[248:249], v[82:83]
	global_load_dwordx4 v[234:237], v[250:251], off offset:3072
	global_load_dwordx4 v[238:241], v[250:251], off offset:3088
	global_load_dwordx4 v[242:245], v[250:251], off offset:3104
	global_load_dwordx4 v[246:249], v[250:251], off offset:3120
	v_add_f32_e32 v80, v81, v80
	v_add_f32_e32 v80, v82, v80
	v_add_f32_e32 v80, v83, v80
	v_fmamk_f32 v80, v80, 0x3a800000, v155
	v_mul_f32_e32 v81, 0x4b800000, v80
	v_cmp_gt_f32_e32 vcc, s47, v80
	v_lshl_add_u64 v[82:83], s[0:1], 0, v[100:101]
	s_nop 0
	v_cndmask_b32_e32 v80, v80, v81, vcc
	v_rsq_f32_e32 v84, v80
	v_lshl_add_u64 v[80:81], v[98:99], 0, s[8:9]
	v_lshl_add_u64 v[80:81], v[80:81], 0, v[136:137]
	v_mul_f32_e32 v85, 0x45800000, v84
	v_cndmask_b32_e32 v84, v84, v85, vcc
	v_pk_mul_f32 v[76:77], v[76:77], v[84:85] op_sel_hi:[1,0]
	v_pk_mul_f32 v[78:79], v[78:79], v[84:85] op_sel_hi:[1,0]
	v_pk_mul_f32 v[72:73], v[72:73], v[84:85] op_sel_hi:[1,0]
	v_pk_mul_f32 v[74:75], v[74:75], v[84:85] op_sel_hi:[1,0]
	v_pk_mul_f32 v[68:69], v[68:69], v[84:85] op_sel_hi:[1,0]
	v_pk_mul_f32 v[70:71], v[70:71], v[84:85] op_sel_hi:[1,0]
	v_pk_mul_f32 v[64:65], v[64:65], v[84:85] op_sel_hi:[1,0]
	v_pk_mul_f32 v[66:67], v[66:67], v[84:85] op_sel_hi:[1,0]
	v_mul_f32_e32 v84, 0xbfb8aa3b, v76
	v_mul_f32_e32 v85, 0xbfb8aa3b, v77
	v_mul_f32_e32 v86, 0xbfb8aa3b, v78
	v_mul_f32_e32 v87, 0xbfb8aa3b, v79
	v_mul_f32_e32 v88, 0xbfb8aa3b, v72
	v_mul_f32_e32 v89, 0xbfb8aa3b, v73
	v_mul_f32_e32 v90, 0xbfb8aa3b, v74
	v_mul_f32_e32 v91, 0xbfb8aa3b, v75
	v_exp_f32_e32 v84, v84
	v_exp_f32_e32 v85, v85
	v_exp_f32_e32 v86, v86
	v_exp_f32_e32 v87, v87
	v_exp_f32_e32 v88, v88
	v_exp_f32_e32 v89, v89
	v_exp_f32_e32 v90, v90
	v_exp_f32_e32 v91, v91
	v_add_f32_e32 v84, 1.0, v84
	v_add_f32_e32 v85, 1.0, v85
	v_add_f32_e32 v86, 1.0, v86
	v_add_f32_e32 v87, 1.0, v87
	v_add_f32_e32 v88, 1.0, v88
	v_add_f32_e32 v89, 1.0, v89
	v_add_f32_e32 v90, 1.0, v90
	v_add_f32_e32 v91, 1.0, v91
	v_rcp_f32_e32 v84, v84
	v_rcp_f32_e32 v85, v85
	v_rcp_f32_e32 v86, v86
	v_rcp_f32_e32 v87, v87
	v_rcp_f32_e32 v88, v88
	v_rcp_f32_e32 v89, v89
	v_rcp_f32_e32 v90, v90
	v_rcp_f32_e32 v91, v91
	v_pk_mul_f32 v[76:77], v[76:77], v[84:85]
	v_pk_mul_f32 v[78:79], v[78:79], v[86:87]
	v_pk_mul_f32 v[72:73], v[72:73], v[88:89]
	v_pk_mul_f32 v[74:75], v[74:75], v[90:91]
	v_pk_mul_f32 v[68:69], v[68:69], v[76:77]
	v_pk_mul_f32 v[70:71], v[70:71], v[78:79]
	v_pk_mul_f32 v[72:73], v[64:65], v[72:73]
	v_pk_mul_f32 v[74:75], v[66:67], v[74:75]
	v_cvt_pk_bf16_f32 v64, v68, v69
	v_cvt_pk_bf16_f32 v65, v70, v71
	v_cvt_pk_bf16_f32 v66, v72, v73
	v_cvt_pk_bf16_f32 v67, v74, v75
	global_store_dwordx4 v[80:81], v[64:67], off nt
	v_mad_i64_i32 v[82:83], s[26:27], v96, s48, v[146:147]
	v_add_u32_e32 v80, 0x90, v148
	v_lshl_add_u64 v[82:83], v[82:83], 0, s[24:25]
	v_ashrrev_i32_e32 v81, 31, v80
	v_lshlrev_b64 v[84:85], 6, v[80:81]
	s_waitcnt vmcnt(16)
	v_pk_add_f32 v[64:65], v[186:187], v[190:191]
	v_pk_add_f32 v[64:65], v[194:195], v[64:65]
	v_pk_add_f32 v[66:67], v[188:189], v[192:193]
	v_pk_add_f32 v[64:65], v[198:199], v[64:65]
	v_pk_add_f32 v[66:67], v[196:197], v[66:67]
	v_add_f32_e32 v64, 0, v64
	v_pk_add_f32 v[66:67], v[200:201], v[66:67]
	v_add_f32_e32 v64, v65, v64
	v_add_f32_e32 v64, v66, v64
	v_add_f32_e32 v64, v67, v64
	v_fmamk_f32 v64, v64, 0x3a800000, v155
	v_mul_f32_e32 v65, 0x4b800000, v64
	v_cmp_gt_f32_e32 vcc, s47, v64
	v_lshl_add_u64 v[66:67], s[0:1], 0, v[84:85]
	s_nop 0
	v_cndmask_b32_e32 v64, v64, v65, vcc
	v_rsq_f32_e32 v68, v64
	v_lshl_add_u64 v[64:65], v[82:83], 0, s[8:9]
	v_lshl_add_u64 v[64:65], v[64:65], 0, v[136:137]
	v_mul_f32_e32 v69, 0x45800000, v68
	v_cndmask_b32_e32 v68, v68, v69, vcc
	v_pk_mul_f32 v[60:61], v[60:61], v[68:69] op_sel_hi:[1,0]
	v_pk_mul_f32 v[62:63], v[62:63], v[68:69] op_sel_hi:[1,0]
	v_pk_mul_f32 v[56:57], v[56:57], v[68:69] op_sel_hi:[1,0]
	v_pk_mul_f32 v[58:59], v[58:59], v[68:69] op_sel_hi:[1,0]
	v_pk_mul_f32 v[52:53], v[52:53], v[68:69] op_sel_hi:[1,0]
	v_pk_mul_f32 v[54:55], v[54:55], v[68:69] op_sel_hi:[1,0]
	v_pk_mul_f32 v[48:49], v[48:49], v[68:69] op_sel_hi:[1,0]
	v_pk_mul_f32 v[50:51], v[50:51], v[68:69] op_sel_hi:[1,0]
	v_mul_f32_e32 v68, 0xbfb8aa3b, v60
	v_mul_f32_e32 v69, 0xbfb8aa3b, v61
	v_mul_f32_e32 v70, 0xbfb8aa3b, v62
	v_mul_f32_e32 v71, 0xbfb8aa3b, v63
	v_mul_f32_e32 v72, 0xbfb8aa3b, v56
	v_mul_f32_e32 v73, 0xbfb8aa3b, v57
	v_mul_f32_e32 v74, 0xbfb8aa3b, v58
	v_mul_f32_e32 v75, 0xbfb8aa3b, v59
	v_exp_f32_e32 v68, v68
	v_exp_f32_e32 v69, v69
	v_exp_f32_e32 v70, v70
	v_exp_f32_e32 v71, v71
	v_exp_f32_e32 v72, v72
	v_exp_f32_e32 v73, v73
	v_exp_f32_e32 v74, v74
	v_exp_f32_e32 v75, v75
	v_add_f32_e32 v68, 1.0, v68
	v_add_f32_e32 v69, 1.0, v69
	v_add_f32_e32 v70, 1.0, v70
	v_add_f32_e32 v71, 1.0, v71
	v_add_f32_e32 v72, 1.0, v72
	v_add_f32_e32 v73, 1.0, v73
	v_add_f32_e32 v74, 1.0, v74
	v_add_f32_e32 v75, 1.0, v75
	v_rcp_f32_e32 v68, v68
	v_rcp_f32_e32 v69, v69
	v_rcp_f32_e32 v70, v70
	v_rcp_f32_e32 v71, v71
	v_rcp_f32_e32 v72, v72
	v_rcp_f32_e32 v73, v73
	v_rcp_f32_e32 v74, v74
	v_rcp_f32_e32 v75, v75
	v_pk_mul_f32 v[60:61], v[60:61], v[68:69]
	v_pk_mul_f32 v[62:63], v[62:63], v[70:71]
	v_pk_mul_f32 v[56:57], v[56:57], v[72:73]
	v_pk_mul_f32 v[58:59], v[58:59], v[74:75]
	v_pk_mul_f32 v[52:53], v[52:53], v[60:61]
	v_pk_mul_f32 v[54:55], v[54:55], v[62:63]
	v_pk_mul_f32 v[56:57], v[48:49], v[56:57]
	v_pk_mul_f32 v[58:59], v[50:51], v[58:59]
	v_cvt_pk_bf16_f32 v48, v52, v53
	v_cvt_pk_bf16_f32 v49, v54, v55
	v_cvt_pk_bf16_f32 v50, v56, v57
	v_cvt_pk_bf16_f32 v51, v58, v59
	global_store_dwordx4 v[64:65], v[48:51], off nt
	v_mad_i64_i32 v[66:67], s[26:27], v80, s48, v[146:147]
	v_add_u32_e32 v64, 0xa0, v148
	v_lshl_add_u64 v[66:67], v[66:67], 0, s[24:25]
	v_ashrrev_i32_e32 v65, 31, v64
	v_lshlrev_b64 v[68:69], 6, v[64:65]
	s_waitcnt vmcnt(12)
; DI unsigned cvtpk(float lo, float hi) { f32x2_t v = {lo, hi}; bf16x2_t b = __builtin_convertvector(v, bf16x2_t); return __builtin_bit_cast(unsigned, b); }
; DI float silu_f(float x) { return x * __builtin_amdgcn_rcpf(1.0f + __expf(-x)); }
;     DI void operator()(const f32x4 (&acc)[2][2][4][2], const Unit& u, int wr, int wc, int fr, int fq) const {
;     ...
;         for (int ai = 0; ai < 2; ++ai)
; #pragma unroll
;             for (int m = 0; m < 4; ++m) {
;                 const int row = u.pm * 256 + 128 * ai + 64 * wr + 16 * m + fr;
;                 const float* sp = SSQ + (size_t)row * 16;
;                 const f32x4 s0 = *(const f32x4*)sp, s1 = *(const f32x4*)(sp + 4), s2 = *(const f32x4*)(sp + 8), s3 = *(const f32x4*)(sp + 12);
;                 float ss = 0.f;
; #pragma unroll
;                 for (int i = 0; i < 4; ++i) ss += s0[i] + s1[i] + s2[i] + s3[i];
;                 const float rs = rsqrtf(ss * (1.0f / DM) + EPS);
;                 float a[8];
; #pragma unroll
;                 for (int n = 0; n < 2; ++n)
; #pragma unroll
;                     for (int t = 0; t < 4; ++t) a[4 * n + t] = silu_f(acc[ai][0][m][n][t] * rs) * (acc[ai][1][m][n][t] * rs);
;                 u32x4 w; w.x = cvtpk(a[0], a[1]); w.y = cvtpk(a[2], a[3]); w.z = cvtpk(a[4], a[5]); w.w = cvtpk(a[6], a[7]);
;                 __builtin_nontemporal_store(w, (u32x4*)(ACT + (size_t)row * DFF + u.pn * 128 + 32 * wc + 8 * fq));
	v_pk_add_f32 v[48:49], v[202:203], v[206:207]
	v_pk_add_f32 v[48:49], v[210:211], v[48:49]
	v_pk_add_f32 v[50:51], v[204:205], v[208:209]
	v_pk_add_f32 v[48:49], v[214:215], v[48:49]
	v_pk_add_f32 v[50:51], v[212:213], v[50:51]
	v_add_f32_e32 v48, 0, v48
	v_pk_add_f32 v[50:51], v[216:217], v[50:51]
	v_add_f32_e32 v48, v49, v48
	v_add_f32_e32 v48, v50, v48
	v_add_f32_e32 v48, v51, v48
	v_fmamk_f32 v48, v48, 0x3a800000, v155
	v_mul_f32_e32 v49, 0x4b800000, v48
	v_cmp_gt_f32_e32 vcc, s47, v48
	v_lshl_add_u64 v[50:51], s[0:1], 0, v[68:69]
	s_nop 0
	v_cndmask_b32_e32 v48, v48, v49, vcc
	v_rsq_f32_e32 v52, v48
	v_lshl_add_u64 v[48:49], v[66:67], 0, s[8:9]
	v_lshl_add_u64 v[48:49], v[48:49], 0, v[136:137]
	v_mul_f32_e32 v53, 0x45800000, v52
	v_cndmask_b32_e32 v52, v52, v53, vcc
	v_pk_mul_f32 v[44:45], v[44:45], v[52:53] op_sel_hi:[1,0]
	v_pk_mul_f32 v[46:47], v[46:47], v[52:53] op_sel_hi:[1,0]
	v_pk_mul_f32 v[40:41], v[40:41], v[52:53] op_sel_hi:[1,0]
	v_pk_mul_f32 v[42:43], v[42:43], v[52:53] op_sel_hi:[1,0]
	v_pk_mul_f32 v[36:37], v[36:37], v[52:53] op_sel_hi:[1,0]
	v_pk_mul_f32 v[38:39], v[38:39], v[52:53] op_sel_hi:[1,0]
	v_pk_mul_f32 v[32:33], v[32:33], v[52:53] op_sel_hi:[1,0]
	v_pk_mul_f32 v[34:35], v[34:35], v[52:53] op_sel_hi:[1,0]
	v_mul_f32_e32 v52, 0xbfb8aa3b, v44
	v_mul_f32_e32 v53, 0xbfb8aa3b, v45
	v_mul_f32_e32 v54, 0xbfb8aa3b, v46
	v_mul_f32_e32 v55, 0xbfb8aa3b, v47
	v_mul_f32_e32 v56, 0xbfb8aa3b, v40
	v_mul_f32_e32 v57, 0xbfb8aa3b, v41
	v_mul_f32_e32 v58, 0xbfb8aa3b, v42
	v_mul_f32_e32 v59, 0xbfb8aa3b, v43
	v_exp_f32_e32 v52, v52
	v_exp_f32_e32 v53, v53
	v_exp_f32_e32 v54, v54
	v_exp_f32_e32 v55, v55
	v_exp_f32_e32 v56, v56
	v_exp_f32_e32 v57, v57
	v_exp_f32_e32 v58, v58
	v_exp_f32_e32 v59, v59
	v_add_f32_e32 v52, 1.0, v52
	v_add_f32_e32 v53, 1.0, v53
	v_add_f32_e32 v54, 1.0, v54
	v_add_f32_e32 v55, 1.0, v55
	v_add_f32_e32 v56, 1.0, v56
	v_add_f32_e32 v57, 1.0, v57
	v_add_f32_e32 v58, 1.0, v58
	v_add_f32_e32 v59, 1.0, v59
	v_rcp_f32_e32 v52, v52
	v_rcp_f32_e32 v53, v53
	v_rcp_f32_e32 v54, v54
	v_rcp_f32_e32 v55, v55
	v_rcp_f32_e32 v56, v56
	v_rcp_f32_e32 v57, v57
	v_rcp_f32_e32 v58, v58
	v_rcp_f32_e32 v59, v59
	v_pk_mul_f32 v[44:45], v[44:45], v[52:53]
	v_pk_mul_f32 v[46:47], v[46:47], v[54:55]
	v_pk_mul_f32 v[40:41], v[40:41], v[56:57]
	v_pk_mul_f32 v[42:43], v[42:43], v[58:59]
	v_pk_mul_f32 v[36:37], v[36:37], v[44:45]
	v_pk_mul_f32 v[38:39], v[38:39], v[46:47]
	v_pk_mul_f32 v[40:41], v[32:33], v[40:41]
	v_pk_mul_f32 v[42:43], v[34:35], v[42:43]
	v_cvt_pk_bf16_f32 v32, v36, v37
	v_cvt_pk_bf16_f32 v33, v38, v39
	v_cvt_pk_bf16_f32 v34, v40, v41
	v_cvt_pk_bf16_f32 v35, v42, v43
	global_store_dwordx4 v[48:49], v[32:35], off nt
	v_mad_i64_i32 v[50:51], s[26:27], v64, s48, v[146:147]
	v_add_u32_e32 v48, 0xb0, v148
	v_lshl_add_u64 v[50:51], v[50:51], 0, s[24:25]
	v_ashrrev_i32_e32 v49, 31, v48
	v_lshlrev_b64 v[52:53], 6, v[48:49]
	s_waitcnt vmcnt(8)
; DI unsigned cvtpk(float lo, float hi) { f32x2_t v = {lo, hi}; bf16x2_t b = __builtin_convertvector(v, bf16x2_t); return __builtin_bit_cast(unsigned, b); }
; DI float silu_f(float x) { return x * __builtin_amdgcn_rcpf(1.0f + __expf(-x)); }
;     DI void operator()(const f32x4 (&acc)[2][2][4][2], const Unit& u, int wr, int wc, int fr, int fq) const {
;     ...
;         for (int ai = 0; ai < 2; ++ai)
; #pragma unroll
;             for (int m = 0; m < 4; ++m) {
;                 const int row = u.pm * 256 + 128 * ai + 64 * wr + 16 * m + fr;
;                 const float* sp = SSQ + (size_t)row * 16;
;                 const f32x4 s0 = *(const f32x4*)sp, s1 = *(const f32x4*)(sp + 4), s2 = *(const f32x4*)(sp + 8), s3 = *(const f32x4*)(sp + 12);
;                 float ss = 0.f;
; #pragma unroll
;                 for (int i = 0; i < 4; ++i) ss += s0[i] + s1[i] + s2[i] + s3[i];
;                 const float rs = rsqrtf(ss * (1.0f / DM) + EPS);
;                 float a[8];
; #pragma unroll
;                 for (int n = 0; n < 2; ++n)
; #pragma unroll
;                     for (int t = 0; t < 4; ++t) a[4 * n + t] = silu_f(acc[ai][0][m][n][t] * rs) * (acc[ai][1][m][n][t] * rs);
;                 u32x4 w; w.x = cvtpk(a[0], a[1]); w.y = cvtpk(a[2], a[3]); w.z = cvtpk(a[4], a[5]); w.w = cvtpk(a[6], a[7]);
;                 __builtin_nontemporal_store(w, (u32x4*)(ACT + (size_t)row * DFF + u.pn * 128 + 32 * wc + 8 * fq));
	v_pk_add_f32 v[32:33], v[218:219], v[222:223]
	v_pk_add_f32 v[32:33], v[226:227], v[32:33]
	v_pk_add_f32 v[34:35], v[220:221], v[224:225]
	v_pk_add_f32 v[32:33], v[230:231], v[32:33]
	v_pk_add_f32 v[34:35], v[228:229], v[34:35]
	v_add_f32_e32 v32, 0, v32
	v_pk_add_f32 v[34:35], v[232:233], v[34:35]
	v_add_f32_e32 v32, v33, v32
	v_add_f32_e32 v32, v34, v32
	v_add_f32_e32 v32, v35, v32
	v_fmamk_f32 v32, v32, 0x3a800000, v155
	v_mul_f32_e32 v33, 0x4b800000, v32
	v_cmp_gt_f32_e32 vcc, s47, v32
	v_lshl_add_u64 v[34:35], s[0:1], 0, v[52:53]
	s_nop 0
	v_cndmask_b32_e32 v32, v32, v33, vcc
	v_rsq_f32_e32 v36, v32
	v_lshl_add_u64 v[32:33], v[50:51], 0, s[8:9]
	v_lshl_add_u64 v[32:33], v[32:33], 0, v[136:137]
	v_mul_f32_e32 v37, 0x45800000, v36
	v_cndmask_b32_e32 v36, v36, v37, vcc
	v_pk_mul_f32 v[28:29], v[28:29], v[36:37] op_sel_hi:[1,0]
	v_pk_mul_f32 v[30:31], v[30:31], v[36:37] op_sel_hi:[1,0]
	v_pk_mul_f32 v[24:25], v[24:25], v[36:37] op_sel_hi:[1,0]
	v_pk_mul_f32 v[26:27], v[26:27], v[36:37] op_sel_hi:[1,0]
	v_pk_mul_f32 v[20:21], v[20:21], v[36:37] op_sel_hi:[1,0]
	v_pk_mul_f32 v[22:23], v[22:23], v[36:37] op_sel_hi:[1,0]
	v_pk_mul_f32 v[16:17], v[16:17], v[36:37] op_sel_hi:[1,0]
	v_pk_mul_f32 v[18:19], v[18:19], v[36:37] op_sel_hi:[1,0]
	v_mul_f32_e32 v36, 0xbfb8aa3b, v28
	v_mul_f32_e32 v37, 0xbfb8aa3b, v29
	v_mul_f32_e32 v38, 0xbfb8aa3b, v30
	v_mul_f32_e32 v39, 0xbfb8aa3b, v31
	v_mul_f32_e32 v40, 0xbfb8aa3b, v24
	v_mul_f32_e32 v41, 0xbfb8aa3b, v25
	v_mul_f32_e32 v42, 0xbfb8aa3b, v26
	v_mul_f32_e32 v43, 0xbfb8aa3b, v27
	v_exp_f32_e32 v36, v36
	v_exp_f32_e32 v37, v37
	v_exp_f32_e32 v38, v38
	v_exp_f32_e32 v39, v39
	v_exp_f32_e32 v40, v40
	v_exp_f32_e32 v41, v41
	v_exp_f32_e32 v42, v42
	v_exp_f32_e32 v43, v43
	v_add_f32_e32 v36, 1.0, v36
	v_add_f32_e32 v37, 1.0, v37
	v_add_f32_e32 v38, 1.0, v38
	v_add_f32_e32 v39, 1.0, v39
	v_add_f32_e32 v40, 1.0, v40
	v_add_f32_e32 v41, 1.0, v41
	v_add_f32_e32 v42, 1.0, v42
	v_add_f32_e32 v43, 1.0, v43
	v_rcp_f32_e32 v36, v36
	v_rcp_f32_e32 v37, v37
	v_rcp_f32_e32 v38, v38
	v_rcp_f32_e32 v39, v39
	v_rcp_f32_e32 v40, v40
	v_rcp_f32_e32 v41, v41
	v_rcp_f32_e32 v42, v42
	v_rcp_f32_e32 v43, v43
	v_pk_mul_f32 v[28:29], v[28:29], v[36:37]
	v_pk_mul_f32 v[30:31], v[30:31], v[38:39]
	v_pk_mul_f32 v[24:25], v[24:25], v[40:41]
	v_pk_mul_f32 v[26:27], v[26:27], v[42:43]
	v_pk_mul_f32 v[20:21], v[20:21], v[28:29]
	v_pk_mul_f32 v[22:23], v[22:23], v[30:31]
	v_pk_mul_f32 v[24:25], v[16:17], v[24:25]
	v_pk_mul_f32 v[26:27], v[18:19], v[26:27]
	v_cvt_pk_bf16_f32 v16, v20, v21
	v_cvt_pk_bf16_f32 v17, v22, v23
	v_cvt_pk_bf16_f32 v18, v24, v25
	v_cvt_pk_bf16_f32 v19, v26, v27
	global_store_dwordx4 v[32:33], v[16:19], off nt
	s_andn2_b64 vcc, exec, s[6:7]
	v_mad_i64_i32 v[32:33], s[26:27], v48, s48, v[146:147]
	s_waitcnt vmcnt(4)
	v_pk_add_f32 v[16:17], v[234:235], v[238:239]
	v_pk_add_f32 v[16:17], v[242:243], v[16:17]
	v_pk_add_f32 v[18:19], v[236:237], v[240:241]
	v_pk_add_f32 v[16:17], v[246:247], v[16:17]
	v_pk_add_f32 v[18:19], v[244:245], v[18:19]
	v_add_f32_e32 v16, 0, v16
	v_pk_add_f32 v[18:19], v[248:249], v[18:19]
	v_add_f32_e32 v16, v17, v16
	v_add_f32_e32 v16, v18, v16
	v_add_f32_e32 v16, v19, v16
	v_fmamk_f32 v16, v16, 0x3a800000, v155
	v_mul_f32_e32 v17, 0x4b800000, v16
	v_cmp_gt_f32_e64 s[6:7], s47, v16
	s_nop 1
	v_cndmask_b32_e64 v16, v16, v17, s[6:7]
	v_rsq_f32_e32 v18, v16
	v_lshl_add_u64 v[16:17], v[32:33], 0, s[24:25]
	v_lshl_add_u64 v[16:17], v[16:17], 0, s[8:9]
	v_lshl_add_u64 v[16:17], v[16:17], 0, v[136:137]
	v_mul_f32_e32 v19, 0x45800000, v18
	v_cndmask_b32_e64 v18, v18, v19, s[6:7]
	v_pk_mul_f32 v[12:13], v[12:13], v[18:19] op_sel_hi:[1,0]
	v_pk_mul_f32 v[14:15], v[14:15], v[18:19] op_sel_hi:[1,0]
	v_pk_mul_f32 v[8:9], v[8:9], v[18:19] op_sel_hi:[1,0]
	v_pk_mul_f32 v[10:11], v[10:11], v[18:19] op_sel_hi:[1,0]
	v_pk_mul_f32 v[4:5], v[4:5], v[18:19] op_sel_hi:[1,0]
	v_pk_mul_f32 v[6:7], v[6:7], v[18:19] op_sel_hi:[1,0]
	v_pk_mul_f32 v[0:1], v[0:1], v[18:19] op_sel_hi:[1,0]
	v_pk_mul_f32 v[2:3], v[2:3], v[18:19] op_sel_hi:[1,0]
	v_mul_f32_e32 v18, 0xbfb8aa3b, v12
	v_mul_f32_e32 v19, 0xbfb8aa3b, v13
	v_mul_f32_e32 v20, 0xbfb8aa3b, v14
	v_mul_f32_e32 v21, 0xbfb8aa3b, v15
	v_mul_f32_e32 v22, 0xbfb8aa3b, v8
	v_mul_f32_e32 v23, 0xbfb8aa3b, v9
	v_mul_f32_e32 v24, 0xbfb8aa3b, v10
	v_mul_f32_e32 v25, 0xbfb8aa3b, v11
	v_exp_f32_e32 v18, v18
	v_exp_f32_e32 v19, v19
	v_exp_f32_e32 v20, v20
	v_exp_f32_e32 v21, v21
	v_exp_f32_e32 v22, v22
	v_exp_f32_e32 v23, v23
	v_exp_f32_e32 v24, v24
	v_exp_f32_e32 v25, v25
	v_add_f32_e32 v18, 1.0, v18
	v_add_f32_e32 v19, 1.0, v19
	v_add_f32_e32 v20, 1.0, v20
	v_add_f32_e32 v21, 1.0, v21
	v_add_f32_e32 v22, 1.0, v22
	v_add_f32_e32 v23, 1.0, v23
	v_add_f32_e32 v24, 1.0, v24
	v_add_f32_e32 v25, 1.0, v25
	v_rcp_f32_e32 v18, v18
	v_rcp_f32_e32 v19, v19
	v_rcp_f32_e32 v20, v20
	v_rcp_f32_e32 v21, v21
	v_rcp_f32_e32 v22, v22
	v_rcp_f32_e32 v23, v23
	v_rcp_f32_e32 v24, v24
	v_rcp_f32_e32 v25, v25
	v_pk_mul_f32 v[12:13], v[12:13], v[18:19]
	v_pk_mul_f32 v[14:15], v[14:15], v[20:21]
	v_pk_mul_f32 v[8:9], v[8:9], v[22:23]
	v_pk_mul_f32 v[10:11], v[10:11], v[24:25]
	v_pk_mul_f32 v[4:5], v[4:5], v[12:13]
	v_pk_mul_f32 v[6:7], v[6:7], v[14:15]
	v_pk_mul_f32 v[8:9], v[0:1], v[8:9]
	v_pk_mul_f32 v[10:11], v[2:3], v[10:11]
	v_cvt_pk_bf16_f32 v0, v4, v5
	v_cvt_pk_bf16_f32 v1, v6, v7
	v_cvt_pk_bf16_f32 v2, v8, v9
	v_cvt_pk_bf16_f32 v3, v10, v11
	s_mov_b64 s[6:7], -1
	global_store_dwordx4 v[16:17], v[0:3], off nt
	s_cbranch_vccnz .LBB0_856
	s_andn2_b64 vcc, exec, s[10:11]
	s_cbranch_vccnz .LBB0_855
	s_barrier
	s_branch .LBB0_855
